# v26 + MoE tile loops: the 24-step scan of moe_find (~390 instr per tile) replaced by a lane-parallel lookup (per-lane gcnt, two DPP row prefix sums, one ballot, three readlanes)
# speedup vs baseline: 1.0119x; 1.0119x over previous
.LBB0_674:
	v_readlane_b32 s8, v237, 56
	v_readlane_b32 s10, v237, 58
	v_readlane_b32 s11, v237, 59
	s_add_i32 s17, s82, s10
	v_cmp_lt_i32_e64 s[10:11], s17, v129
	s_and_b64 s[0:1], s[10:11], exec
	s_cselect_b32 s83, s17, s82
	s_ashr_i32 s2, s83, 3
	s_cmp_gt_i32 s2, -1
	s_cselect_b64 s[0:1], -1, 0
	s_lshl_b32 s4, s2, 7
	v_readlane_b32 s9, v237, 57
	v_cmp_ge_i32_e64 s[8:9], s17, v129
	v_mbcnt_lo_u32_b32 v238, -1, 0
	v_mbcnt_hi_u32_b32 v238, -1, v238
	v_min_u32_e32 v239, 23, v238
	v_lshlrev_b32_e32 v239, 2, v239
	global_load_dword v240, v239, s[92:93]
	v_cmp_gt_u32_e32 vcc, 24, v238
	s_waitcnt vmcnt(0)
	s_nop 1
	v_cndmask_b32_e32 v240, 0, v240, vcc
	v_add_u32_e32 v241, 0x7f, v240
	v_ashrrev_i32_e32 v241, 7, v241
	v_mov_b32_e32 v242, v241
	v_mov_b32_e32 v243, v240
	s_nop 1
	v_add_u32_dpp v242, v242, v242 row_shr:1 row_mask:0xf bank_mask:0xf
	v_add_u32_dpp v243, v243, v243 row_shr:1 row_mask:0xf bank_mask:0xf
	s_nop 1
	v_add_u32_dpp v242, v242, v242 row_shr:2 row_mask:0xf bank_mask:0xf
	v_add_u32_dpp v243, v243, v243 row_shr:2 row_mask:0xf bank_mask:0xf
	s_nop 1
	v_add_u32_dpp v242, v242, v242 row_shr:4 row_mask:0xf bank_mask:0xf
	v_add_u32_dpp v243, v243, v243 row_shr:4 row_mask:0xf bank_mask:0xf
	s_nop 1
	v_add_u32_dpp v242, v242, v242 row_shr:8 row_mask:0xf bank_mask:0xf
	v_add_u32_dpp v243, v243, v243 row_shr:8 row_mask:0xf bank_mask:0xf
	s_nop 1
	v_readlane_b32 s98, v242, 15
	v_readlane_b32 s99, v243, 15
	v_cmp_lt_u32_e32 vcc, 15, v238
	s_nop 1
	v_mov_b32_e32 v244, s98
	v_mov_b32_e32 v245, s99
	v_cndmask_b32_e32 v244, 0, v244, vcc
	v_cndmask_b32_e32 v245, 0, v245, vcc
	v_add_u32_e32 v242, v242, v244
	v_add_u32_e32 v243, v243, v245
	v_sub_u32_e32 v246, v242, v241
	v_sub_u32_e32 v247, v243, v240
	v_cmp_le_i32_e64 s[98:99], v246, s2
	v_cmp_gt_i32_e64 s[100:101], v242, s2
	s_nop 1
	s_and_b64 s[98:99], s[98:99], s[100:101]
	s_ff1_i32_b64 s98, s[98:99]
	s_max_i32 s98, s98, 0
	s_nop 3
	v_readlane_b32 s99, v246, s98
	v_readlane_b32 s100, v240, s98
	v_readlane_b32 s101, v247, s98
	s_sub_i32 s99, s2, s99
	s_lshl_b32 s99, s99, 7
	v_mov_b32_e32 v134, s98
	v_mov_b32_e32 v150, s99
	v_mov_b32_e32 v151, s100
	v_mov_b32_e32 v152, s101
	v_readlane_b32 s12, v237, 25
	v_readlane_b32 s13, v237, 26
	v_readlane_b32 s0, v237, 62
	v_readlane_b32 s1, v237, 63
	v_readlane_b32 s0, v237, 60
	v_readlane_b32 s1, v237, 61

.LBB0_814:
	v_readlane_b32 s8, v237, 56
	v_readlane_b32 s10, v237, 58
	v_readlane_b32 s11, v237, 59
	s_add_i32 s17, s16, s10
	v_cmp_lt_i32_e64 s[10:11], s17, v129
	s_and_b64 s[0:1], s[10:11], exec
	s_cselect_b32 s33, s17, s16
	s_ashr_i32 s2, s33, 3
	s_cmp_gt_i32 s2, -1
	s_cselect_b64 s[0:1], -1, 0
	s_lshl_b32 s12, s2, 7
	v_readlane_b32 s9, v237, 57
	v_cmp_ge_i32_e64 s[8:9], s17, v129
	v_mbcnt_lo_u32_b32 v238, -1, 0
	v_mbcnt_hi_u32_b32 v238, -1, v238
	v_min_u32_e32 v239, 23, v238
	v_lshlrev_b32_e32 v239, 2, v239
	global_load_dword v240, v239, s[92:93]
	v_cmp_gt_u32_e32 vcc, 24, v238
	s_waitcnt vmcnt(0)
	s_nop 1
	v_cndmask_b32_e32 v240, 0, v240, vcc
	v_add_u32_e32 v241, 0x7f, v240
	v_ashrrev_i32_e32 v241, 7, v241
	v_mov_b32_e32 v242, v241
	v_mov_b32_e32 v243, v240
	s_nop 1
	v_add_u32_dpp v242, v242, v242 row_shr:1 row_mask:0xf bank_mask:0xf
	v_add_u32_dpp v243, v243, v243 row_shr:1 row_mask:0xf bank_mask:0xf
	s_nop 1
	v_add_u32_dpp v242, v242, v242 row_shr:2 row_mask:0xf bank_mask:0xf
	v_add_u32_dpp v243, v243, v243 row_shr:2 row_mask:0xf bank_mask:0xf
	s_nop 1
	v_add_u32_dpp v242, v242, v242 row_shr:4 row_mask:0xf bank_mask:0xf
	v_add_u32_dpp v243, v243, v243 row_shr:4 row_mask:0xf bank_mask:0xf
	s_nop 1
	v_add_u32_dpp v242, v242, v242 row_shr:8 row_mask:0xf bank_mask:0xf
	v_add_u32_dpp v243, v243, v243 row_shr:8 row_mask:0xf bank_mask:0xf
	s_nop 1
	v_readlane_b32 s98, v242, 15
	v_readlane_b32 s99, v243, 15
	v_cmp_lt_u32_e32 vcc, 15, v238
	s_nop 1
	v_mov_b32_e32 v244, s98
	v_mov_b32_e32 v245, s99
	v_cndmask_b32_e32 v244, 0, v244, vcc
	v_cndmask_b32_e32 v245, 0, v245, vcc
	v_add_u32_e32 v242, v242, v244
	v_add_u32_e32 v243, v243, v245
	v_sub_u32_e32 v246, v242, v241
	v_sub_u32_e32 v247, v243, v240
	v_cmp_le_i32_e64 s[98:99], v246, s2
	v_cmp_gt_i32_e64 s[100:101], v242, s2
	s_nop 1
	s_and_b64 s[98:99], s[98:99], s[100:101]
	s_ff1_i32_b64 s98, s[98:99]
	s_max_i32 s98, s98, 0
	s_nop 3
	v_readlane_b32 s99, v246, s98
	v_readlane_b32 s100, v240, s98
	v_readlane_b32 s101, v247, s98
	s_sub_i32 s99, s2, s99
	s_lshl_b32 s99, s99, 7
	v_mov_b32_e32 v146, s98
	v_mov_b32_e32 v145, s99
	v_mov_b32_e32 v147, s100
	v_mov_b32_e32 v64, s101
	v_readlane_b32 s18, v237, 27
	v_readlane_b32 s19, v237, 28
	v_readlane_b32 s0, v237, 62
	v_readlane_b32 s1, v237, 63
	v_readlane_b32 s0, v237, 60
	v_readlane_b32 s1, v237, 61

.LBB0_1798:
	v_readlane_b32 s4, v237, 56
	v_readlane_b32 s6, v237, 58
	v_readlane_b32 s7, v237, 59
	s_add_i32 s17, s60, s6
	v_cmp_lt_i32_e64 s[6:7], s17, v129
	s_and_b64 s[0:1], s[6:7], exec
	s_cselect_b32 s61, s17, s60
	s_ashr_i32 s94, s61, 3
	s_cmp_gt_i32 s94, -1
	s_cselect_b64 s[0:1], -1, 0
	s_lshl_b32 s8, s94, 7
	v_readlane_b32 s5, v237, 57
	v_cmp_ge_i32_e64 s[4:5], s17, v129
	v_mbcnt_lo_u32_b32 v238, -1, 0
	v_mbcnt_hi_u32_b32 v238, -1, v238
	v_min_u32_e32 v239, 23, v238
	v_lshlrev_b32_e32 v239, 2, v239
	global_load_dword v240, v239, s[2:3]
	v_cmp_gt_u32_e32 vcc, 24, v238
	s_waitcnt vmcnt(0)
	s_nop 1
	v_cndmask_b32_e32 v240, 0, v240, vcc
	v_add_u32_e32 v241, 0x7f, v240
	v_ashrrev_i32_e32 v241, 7, v241
	v_mov_b32_e32 v242, v241
	v_mov_b32_e32 v243, v240
	s_nop 1
	v_add_u32_dpp v242, v242, v242 row_shr:1 row_mask:0xf bank_mask:0xf
	v_add_u32_dpp v243, v243, v243 row_shr:1 row_mask:0xf bank_mask:0xf
	s_nop 1
	v_add_u32_dpp v242, v242, v242 row_shr:2 row_mask:0xf bank_mask:0xf
	v_add_u32_dpp v243, v243, v243 row_shr:2 row_mask:0xf bank_mask:0xf
	s_nop 1
	v_add_u32_dpp v242, v242, v242 row_shr:4 row_mask:0xf bank_mask:0xf
	v_add_u32_dpp v243, v243, v243 row_shr:4 row_mask:0xf bank_mask:0xf
	s_nop 1
	v_add_u32_dpp v242, v242, v242 row_shr:8 row_mask:0xf bank_mask:0xf
	v_add_u32_dpp v243, v243, v243 row_shr:8 row_mask:0xf bank_mask:0xf
	s_nop 1
	v_readlane_b32 s98, v242, 15
	v_readlane_b32 s99, v243, 15
	v_cmp_lt_u32_e32 vcc, 15, v238
	s_nop 1
	v_mov_b32_e32 v244, s98
	v_mov_b32_e32 v245, s99
	v_cndmask_b32_e32 v244, 0, v244, vcc
	v_cndmask_b32_e32 v245, 0, v245, vcc
	v_add_u32_e32 v242, v242, v244
	v_add_u32_e32 v243, v243, v245
	v_sub_u32_e32 v246, v242, v241
	v_sub_u32_e32 v247, v243, v240
	v_cmp_le_i32_e64 s[98:99], v246, s94
	v_cmp_gt_i32_e64 s[100:101], v242, s94
	s_nop 1
	s_and_b64 s[98:99], s[98:99], s[100:101]
	s_ff1_i32_b64 s98, s[98:99]
	s_max_i32 s98, s98, 0
	s_nop 3
	v_readlane_b32 s99, v246, s98
	v_readlane_b32 s100, v240, s98
	v_readlane_b32 s101, v247, s98
	s_sub_i32 s99, s94, s99
	s_lshl_b32 s99, s99, 7
	v_mov_b32_e32 v134, s98
	v_mov_b32_e32 v149, s99
	v_mov_b32_e32 v150, s100
	v_mov_b32_e32 v151, s101

.LBB0_1938:
	v_readlane_b32 s4, v237, 56
	v_readlane_b32 s6, v237, 58
	v_readlane_b32 s0, v237, 31
	v_readlane_b32 s7, v237, 59
	s_add_i32 s61, s0, s6
	v_readlane_b32 s1, v237, 32
	v_cmp_lt_i32_e64 s[6:7], s61, v129
	s_mov_b32 s8, s0
	s_and_b64 s[0:1], s[6:7], exec
	s_cselect_b32 s92, s61, s8
	s_ashr_i32 s94, s92, 3
	s_cmp_gt_i32 s94, -1
	s_cselect_b64 s[0:1], -1, 0
	s_lshl_b32 s8, s94, 7
	v_readlane_b32 s5, v237, 57
	v_cmp_ge_i32_e64 s[4:5], s61, v129
	v_mbcnt_lo_u32_b32 v238, -1, 0
	v_mbcnt_hi_u32_b32 v238, -1, v238
	v_min_u32_e32 v239, 23, v238
	v_lshlrev_b32_e32 v239, 2, v239
	global_load_dword v240, v239, s[2:3]
	v_cmp_gt_u32_e32 vcc, 24, v238
	s_waitcnt vmcnt(0)
	s_nop 1
	v_cndmask_b32_e32 v240, 0, v240, vcc
	v_add_u32_e32 v241, 0x7f, v240
	v_ashrrev_i32_e32 v241, 7, v241
	v_mov_b32_e32 v242, v241
	v_mov_b32_e32 v243, v240
	s_nop 1
	v_add_u32_dpp v242, v242, v242 row_shr:1 row_mask:0xf bank_mask:0xf
	v_add_u32_dpp v243, v243, v243 row_shr:1 row_mask:0xf bank_mask:0xf
	s_nop 1
	v_add_u32_dpp v242, v242, v242 row_shr:2 row_mask:0xf bank_mask:0xf
	v_add_u32_dpp v243, v243, v243 row_shr:2 row_mask:0xf bank_mask:0xf
	s_nop 1
	v_add_u32_dpp v242, v242, v242 row_shr:4 row_mask:0xf bank_mask:0xf
	v_add_u32_dpp v243, v243, v243 row_shr:4 row_mask:0xf bank_mask:0xf
	s_nop 1
	v_add_u32_dpp v242, v242, v242 row_shr:8 row_mask:0xf bank_mask:0xf
	v_add_u32_dpp v243, v243, v243 row_shr:8 row_mask:0xf bank_mask:0xf
	s_nop 1
	v_readlane_b32 s98, v242, 15
	v_readlane_b32 s99, v243, 15
	v_cmp_lt_u32_e32 vcc, 15, v238
	s_nop 1
	v_mov_b32_e32 v244, s98
	v_mov_b32_e32 v245, s99
	v_cndmask_b32_e32 v244, 0, v244, vcc
	v_cndmask_b32_e32 v245, 0, v245, vcc
	v_add_u32_e32 v242, v242, v244
	v_add_u32_e32 v243, v243, v245
	v_sub_u32_e32 v246, v242, v241
	v_sub_u32_e32 v247, v243, v240
	v_cmp_le_i32_e64 s[98:99], v246, s94
	v_cmp_gt_i32_e64 s[100:101], v242, s94
	s_nop 1
	s_and_b64 s[98:99], s[98:99], s[100:101]
	s_ff1_i32_b64 s98, s[98:99]
	s_max_i32 s98, s98, 0
	s_nop 3
	v_readlane_b32 s99, v246, s98
	v_readlane_b32 s100, v240, s98
	v_readlane_b32 s101, v247, s98
	s_sub_i32 s99, s94, s99
	s_lshl_b32 s99, s99, 7
	v_mov_b32_e32 v146, s98
	v_mov_b32_e32 v145, s99
	v_mov_b32_e32 v147, s100
	v_mov_b32_e32 v64, s101
